# cross-attention V staging (prompt unit stage_t and sample unit f32 stream): lane remap so 4 adjacent lanes read one contiguous row segment
# speedup vs baseline: 1.0190x; 1.0069x over previous
.LBB0_148:
	v_mov_b32_e32 v189, 0x260
	s_and_b64 vcc, exec, s[4:5]
	s_cbranch_vccz .LBB0_185
	v_and_b32_e32 v50, 3, v191
	v_lshrrev_b32_e32 v51, 2, v191
	v_lshl_or_b32 v50, v50, 7, v51
	v_add_u32_e32 v51, 0x200, v50
	v_add_u32_e32 v52, 0x400, v50
	v_add_u32_e32 v53, 0x600, v50
	v_readlane_b32 s6, v254, 59
	s_lshl_b32 s0, s6, 11
	s_lshl_b32 s4, s72, 6
	s_add_i32 s4, s0, s4
	s_ashr_i32 s5, s4, 31
	s_lshl_b64 s[4:5], s[4:5], 2
	s_add_u32 s10, s38, s4
	s_addc_u32 s11, s39, s5
	s_cmp_lg_u32 s6, 0
	v_readlane_b32 s0, v252, 11
	s_cselect_b32 s6, s0, 0
	s_cmp_lg_u32 s6, 2
	v_and_b32_e32 v11, 15, v191
	v_readlane_b32 s21, v254, 58
	s_cselect_b64 s[12:13], -1, 0
	s_and_b64 s[4:5], s[96:97], exec
	v_lshl_or_b32 v1, s21, 5, v11
	s_movk_i32 s0, 0x90
	s_cselect_b32 s52, 0x80, 0
	v_mul_lo_u32 v1, v1, s0
	s_and_b32 s0, s69, 0xffffffc0
	v_mov_b32_e32 v0, 0x4000
	s_cmp_lt_i32 s21, 4
	v_and_or_b32 v97, v191, 7, v0
	v_lshrrev_b32_e32 v0, 4, v192
	s_cselect_b64 s[14:15], -1, 0
	s_lshl_b32 s16, s21, 4
	v_ashrrev_i32_e32 v2, 31, v191
	v_lshlrev_b32_e32 v96, 3, v0
	v_or_b32_e32 v176, s16, v11
	s_movk_i32 s20, 0x210
	s_ashr_i32 s17, s16, 31
	v_lshlrev_b32_e32 v98, 2, v0
	v_lshrrev_b32_e32 v0, 28, v2
	v_add_u32_e32 v12, 0, v1
	v_mul_lo_u32 v1, v176, s20
	s_cmp_lg_u32 s6, 1
	v_add_u32_e32 v0, v191, v0
	v_add_u32_e32 v15, 0, v1
	s_cselect_b64 s[18:19], -1, 0
	s_and_b64 s[6:7], s[96:97], exec
	v_and_b32_e32 v1, -16, v0
	v_ashrrev_i32_e32 v0, 4, v0
	v_sub_u32_e32 v3, v191, v1
	v_ashrrev_i32_e32 v1, 31, v0
	s_movk_i32 s7, 0x110
	v_add_u32_e32 v4, 0x200, v191
	v_lshlrev_b64 v[100:101], 12, v[0:1]
	v_mul_lo_u32 v0, v0, s7
	v_ashrrev_i32_e32 v5, 31, v4
	v_add_u32_e32 v16, 0, v0
	v_lshrrev_b32_e32 v0, 28, v5
	v_add_u32_e32 v1, v4, v0
	v_ashrrev_i32_e32 v0, 4, v1
	v_and_b32_e32 v1, -16, v1
	v_lshlrev_b32_e32 v102, 3, v3
	v_lshlrev_b32_e32 v17, 4, v3
	v_sub_u32_e32 v3, v4, v1
	v_ashrrev_i32_e32 v1, 31, v0
	v_add_u32_e32 v6, 0x400, v191
	v_lshlrev_b64 v[104:105], 12, v[0:1]
	v_mul_lo_u32 v0, v0, s7
	v_ashrrev_i32_e32 v7, 31, v6
	v_add_u32_e32 v18, 0, v0
	v_lshrrev_b32_e32 v0, 28, v7
	v_add_u32_e32 v1, v6, v0
	v_ashrrev_i32_e32 v0, 4, v1
	v_and_b32_e32 v1, -16, v1
	v_lshlrev_b32_e32 v106, 3, v3
	v_lshlrev_b32_e32 v19, 4, v3
	v_sub_u32_e32 v3, v6, v1
	v_ashrrev_i32_e32 v1, 31, v0
	v_add_u32_e32 v8, 0x600, v191
	v_lshlrev_b64 v[108:109], 12, v[0:1]
	v_mul_lo_u32 v0, v0, s7
	v_ashrrev_i32_e32 v9, 31, v8
	v_add_u32_e32 v20, 0, v0
	v_lshrrev_b32_e32 v0, 28, v9
	v_add_u32_e32 v1, v8, v0
	v_ashrrev_i32_e32 v0, 4, v1
	v_and_b32_e32 v1, -16, v1
	v_lshlrev_b32_e32 v110, 3, v3
	v_lshlrev_b32_e32 v21, 4, v3
	v_sub_u32_e32 v3, v8, v1
	v_ashrrev_i32_e32 v1, 31, v0
	v_lshlrev_b64 v[112:113], 12, v[0:1]
	v_mul_lo_u32 v0, v0, s7
	v_add_u32_e32 v1, 0x800, v191
	v_add_u32_e32 v22, 0, v0
	v_ashrrev_i32_e32 v0, 31, v1
	v_lshrrev_b32_e32 v0, 28, v0
	v_lshlrev_b32_e32 v114, 3, v3
	v_lshlrev_b32_e32 v23, 4, v3
	v_add_u32_e32 v3, v1, v0
	v_ashrrev_i32_e32 v0, 4, v3
	v_and_b32_e32 v3, -16, v3
	v_sub_u32_e32 v3, v1, v3
	v_ashrrev_i32_e32 v1, 31, v0
	v_lshlrev_b64 v[116:117], 12, v[0:1]
	v_mul_lo_u32 v0, v0, s7
	v_add_u32_e32 v1, 0xa00, v191
	v_add_u32_e32 v24, 0, v0
	v_ashrrev_i32_e32 v0, 31, v1
	v_lshrrev_b32_e32 v0, 28, v0
	v_lshlrev_b32_e32 v118, 3, v3
	v_lshlrev_b32_e32 v25, 4, v3
	v_add_u32_e32 v3, v1, v0
	v_ashrrev_i32_e32 v0, 4, v3
	v_and_b32_e32 v3, -16, v3
	v_sub_u32_e32 v3, v1, v3
	v_ashrrev_i32_e32 v1, 31, v0
	v_lshlrev_b64 v[120:121], 12, v[0:1]
	v_mul_lo_u32 v0, v0, s7
	v_add_u32_e32 v1, 0xc00, v191
	v_add_u32_e32 v26, 0, v0
	v_ashrrev_i32_e32 v0, 31, v1
	v_lshrrev_b32_e32 v0, 28, v0
	v_lshlrev_b32_e32 v122, 3, v3
	v_lshlrev_b32_e32 v27, 4, v3
	v_add_u32_e32 v3, v1, v0
	v_ashrrev_i32_e32 v0, 4, v3
	v_and_b32_e32 v3, -16, v3
	v_sub_u32_e32 v3, v1, v3
	v_ashrrev_i32_e32 v1, 31, v0
	v_lshlrev_b64 v[124:125], 12, v[0:1]
	v_mul_lo_u32 v0, v0, s7
	v_add_u32_e32 v1, 0xe00, v191
	v_add_u32_e32 v28, 0, v0
	v_ashrrev_i32_e32 v0, 31, v1
	v_lshrrev_b32_e32 v0, 28, v0
	v_lshlrev_b32_e32 v126, 3, v3
	v_lshlrev_b32_e32 v29, 4, v3
	v_add_u32_e32 v3, v1, v0
	v_ashrrev_i32_e32 v0, 4, v3
	v_and_b32_e32 v3, -16, v3
	v_sub_u32_e32 v3, v1, v3
	v_ashrrev_i32_e32 v1, 31, v0
	s_mul_i32 s6, s21, 0x2100
	v_lshlrev_b64 v[128:129], 12, v[0:1]
	v_mul_lo_u32 v0, v0, s7
	s_cselect_b32 s53, 0x800000, 0
	v_add_u32_e32 v30, 0, v0
	v_or_b32_e32 v0, 0xb0, v192
	s_add_i32 s6, s6, 0
	v_mul_u32_u24_e32 v39, 0x110, v0
	v_or_b32_e32 v0, 0xf0, v192
	s_add_i32 s7, s6, 0x11000
	v_mul_u32_u24_e32 v40, 0x110, v0
	v_mov_b32_e32 v0, s7
	v_mad_u32_u24 v41, v11, s20, v0
	v_lshrrev_b32_e32 v0, 25, v2
	v_add_u32_e32 v0, v50, v0
	v_ashrrev_i32_e32 v42, 7, v0
	v_and_b32_e32 v0, 0xffffff80, v0
	v_sub_u32_e32 v43, v50, v0
	v_lshlrev_b32_e32 v0, 1, v43
	v_ashrrev_i32_e32 v1, 31, v0
	v_lshlrev_b64 v[132:133], 12, v[0:1]
	v_or_b32_e32 v0, 1, v0
	v_ashrrev_i32_e32 v1, 31, v0
	s_movk_i32 s7, 0x1080
	v_lshlrev_b64 v[134:135], 12, v[0:1]
	v_mul_lo_u32 v0, v42, s7
	v_lshlrev_b32_e32 v2, 3, v42
	v_add_u32_e32 v42, 0, v0
	v_lshrrev_b32_e32 v0, 25, v5
	v_add_u32_e32 v0, v51, v0
	v_ashrrev_i32_e32 v44, 7, v0
	v_and_b32_e32 v0, 0xffffff80, v0
	v_sub_u32_e32 v45, v51, v0
	v_lshlrev_b32_e32 v0, 1, v45
	v_ashrrev_i32_e32 v1, 31, v0
	v_lshlrev_b64 v[136:137], 12, v[0:1]
	v_or_b32_e32 v0, 1, v0
	v_ashrrev_i32_e32 v1, 31, v0
	v_lshlrev_b64 v[138:139], 12, v[0:1]
	v_mul_lo_u32 v0, v44, s7
	v_lshlrev_b32_e32 v4, 3, v44
	v_add_u32_e32 v44, 0, v0
	v_lshrrev_b32_e32 v0, 25, v7
	v_add_u32_e32 v0, v52, v0
	v_ashrrev_i32_e32 v46, 7, v0
	v_and_b32_e32 v0, 0xffffff80, v0
	v_sub_u32_e32 v47, v52, v0
	v_lshlrev_b32_e32 v0, 1, v47
	v_ashrrev_i32_e32 v1, 31, v0
	v_lshlrev_b64 v[140:141], 12, v[0:1]
	v_or_b32_e32 v0, 1, v0
	v_ashrrev_i32_e32 v1, 31, v0
	v_lshlrev_b64 v[142:143], 12, v[0:1]
	v_mul_lo_u32 v0, v46, s7
	v_lshlrev_b32_e32 v6, 3, v46
	v_add_u32_e32 v46, 0, v0
	v_lshrrev_b32_e32 v0, 25, v9
	v_add_u32_e32 v0, v53, v0
	v_ashrrev_i32_e32 v48, 7, v0
	v_and_b32_e32 v0, 0xffffff80, v0
	v_sub_u32_e32 v49, v53, v0
	v_lshlrev_b32_e32 v0, 1, v49
	v_ashrrev_i32_e32 v1, 31, v0
	v_lshlrev_b64 v[144:145], 12, v[0:1]
	v_or_b32_e32 v0, 1, v0
	v_lshl_add_u32 v174, v11, 2, 0
	s_movk_i32 s4, 0x20c
	v_ashrrev_i32_e32 v1, 31, v0
	v_mad_u32_u24 v175, v11, s4, v174
	v_lshlrev_b64 v[146:147], 12, v[0:1]
	v_mul_lo_u32 v0, v48, s7
	v_and_b32_e32 v99, 48, v191
	s_waitcnt lgkmcnt(0)
	v_add_u32_e32 v13, s0, v175
	v_or_b32_e32 v34, 16, v11
	v_or_b32_e32 v35, 48, v192
	v_or_b32_e32 v37, 0x70, v192
	v_lshlrev_b32_e32 v8, 3, v48
	v_add_u32_e32 v0, 0, v0
	v_lshlrev_b32_e32 v1, 2, v49
	v_lshl_add_u32 v10, v192, 2, 0
	v_mul_i32_i24_e32 v14, 0xfffffdf4, v11
	v_cmp_gt_u32_e64 s[4:5], 8, v11
	v_lshlrev_b32_e32 v130, 3, v3
	v_lshlrev_b32_e32 v31, 4, v3
	v_add_u32_e32 v32, 0, v99
	v_mul_u32_u24_e32 v33, 0x110, v11
	v_mul_u32_u24_e32 v36, 0x110, v35
	v_mul_u32_u24_e32 v38, 0x110, v37
	v_ashrrev_i32_e32 v3, 31, v2
	v_lshlrev_b32_e32 v43, 2, v43
	v_ashrrev_i32_e32 v5, 31, v4
	v_lshlrev_b32_e32 v45, 2, v45
	v_ashrrev_i32_e32 v7, 31, v6
	v_lshlrev_b32_e32 v47, 2, v47
	v_ashrrev_i32_e32 v9, 31, v8
	v_mul_u32_u24_e32 v34, 0x210, v34
	v_mul_u32_u24_e32 v35, 0x210, v35
	v_mul_u32_u24_e32 v37, 0x210, v37
	v_mad_u32_u24 v11, v11, s20, v99
	v_add_u32_e32 v211, v0, v1
	v_add_u32_e32 v0, v13, v96
	v_cmp_gt_u32_e64 s[8:9], 16, v192
	v_ashrrev_i32_e32 v103, 31, v102
	v_ashrrev_i32_e32 v107, 31, v106
	v_ashrrev_i32_e32 v111, 31, v110
	v_ashrrev_i32_e32 v115, 31, v114
	v_ashrrev_i32_e32 v119, 31, v118
	v_ashrrev_i32_e32 v123, 31, v122
	v_ashrrev_i32_e32 v127, 31, v126
	v_ashrrev_i32_e32 v131, 31, v130
	v_add_u32_e32 v177, 0, v11
	v_add3_u32 v178, v34, v99, 0
	v_add3_u32 v179, v35, v99, 0
	v_add3_u32 v180, v37, v99, 0
	v_add_u32_e32 v181, s6, v11
	v_add_u32_e32 v193, v12, v99
	v_add_u32_e32 v194, v175, v14
	v_add_u32_e32 v195, v16, v17
	v_add_u32_e32 v196, v18, v19
	v_add_u32_e32 v197, v20, v21
	v_add_u32_e32 v198, v22, v23
	v_add_u32_e32 v199, v24, v25
	v_add_u32_e32 v200, v26, v27
	v_add_u32_e32 v201, v28, v29
	v_add_u32_e32 v202, v30, v31
	v_add_u32_e32 v203, v32, v33
	v_add_u32_e32 v204, v32, v36
	v_add_u32_e32 v205, v32, v38
	v_add_u32_e32 v206, v32, v39
	v_add_u32_e32 v207, v32, v40
	v_lshlrev_b64 v[148:149], 1, v[2:3]
	v_add_u32_e32 v208, v42, v43
	v_lshlrev_b64 v[150:151], 1, v[4:5]
	v_add_u32_e32 v209, v44, v45
	v_lshlrev_b64 v[158:159], 1, v[6:7]
	v_add_u32_e32 v210, v46, v47
	v_lshlrev_b64 v[160:161], 1, v[8:9]
	v_add_u32_e32 v212, s0, v10
	v_add_u32_e32 v213, 0x9000, v0
	v_add_u32_e32 v214, v15, v99
	v_add_u32_e32 v215, v41, v96
	s_branch .LBB0_152

.LBB0_154:
	s_or_b64 exec, exec, s[6:7]
	v_mov_b32_e32 v0, s86
	s_waitcnt lgkmcnt(0)
	s_barrier
	ds_read_b32 v0, v0
	s_mov_b64 s[6:7], -1
	s_waitcnt lgkmcnt(0)
	v_cmp_lt_i32_e32 vcc, s58, v0
	v_readfirstlane_b32 s24, v0
	s_cbranch_vccnz .LBB0_151
	s_bitcmp0_b32 s24, 0
	s_cbranch_scc1 .LBB0_179
	s_andn2_b64 vcc, exec, s[12:13]
	s_cbranch_vccnz .LBB0_178
	s_ashr_i32 s0, s24, 3
	s_add_i32 s20, s0, s52
	s_mov_b32 s71, s69
	s_mov_b64 s[68:69], s[76:77]
	s_mov_b64 s[66:67], s[78:79]
	s_mov_b64 s[64:65], s[80:81]
	s_ashr_i32 s21, s20, 31
	v_readlane_b32 s72, v253, 42
	s_and_b32 s25, s24, -8
	s_lshl_b64 s[22:23], s[20:21], 20
	v_readlane_b32 s82, v253, 52
	v_readlane_b32 s83, v253, 53
	s_add_u32 s21, s82, s22
	s_addc_u32 s55, s83, s23
	s_lshl_b32 s0, s24, 7
	s_and_b32 s0, s0, 0x300
	s_mov_b64 s[6:7], s[94:95]
	v_mov_b32_e32 v216, v191
	s_lshl_b32 s20, s0, 2
	s_add_u32 s54, s21, s20
	v_lshlrev_b32_e32 v0, 5, v216
	v_ashrrev_i32_e32 v74, 3, v216
	v_add_u32_e32 v217, 0x200, v216
	s_addc_u32 s55, s55, 0
	v_and_b32_e32 v152, 0xe0, v0
	v_ashrrev_i32_e32 v75, 31, v74
	v_ashrrev_i32_e32 v76, 3, v217
	v_lshl_add_u64 v[0:1], s[54:55], 0, v[152:153]
	v_lshlrev_b64 v[2:3], 12, v[74:75]
	v_ashrrev_i32_e32 v77, 31, v76
	v_lshl_add_u64 v[32:33], v[0:1], 0, v[2:3]
	v_lshlrev_b64 v[2:3], 12, v[76:77]
	v_lshl_add_u64 v[34:35], v[0:1], 0, v[2:3]
	v_add_u32_e32 v2, 0x400, v216
	v_ashrrev_i32_e32 v78, 3, v2
	v_ashrrev_i32_e32 v79, 31, v78
	v_lshlrev_b64 v[2:3], 12, v[78:79]
	v_lshl_add_u64 v[36:37], v[0:1], 0, v[2:3]
	v_add_u32_e32 v2, 0x600, v216
	v_ashrrev_i32_e32 v80, 3, v2
	v_ashrrev_i32_e32 v81, 31, v80
	global_load_dwordx4 v[42:45], v[32:33], off offset:16
	global_load_dwordx4 v[46:49], v[32:33], off
	global_load_dwordx4 v[50:53], v[34:35], off offset:16
	global_load_dwordx4 v[54:57], v[34:35], off
	v_lshlrev_b64 v[2:3], 12, v[80:81]
	global_load_dwordx4 v[58:61], v[36:37], off offset:16
	global_load_dwordx4 v[62:65], v[36:37], off
	v_lshl_add_u64 v[38:39], v[0:1], 0, v[2:3]
	global_load_dwordx4 v[66:69], v[38:39], off offset:16
	global_load_dwordx4 v[70:73], v[38:39], off
	v_lshlrev_b32_e32 v41, 4, v216
	v_add_u32_e32 v40, s25, v97
	v_and_b32_e32 v41, 0x70, v41
	v_readlane_b32 s84, v253, 54
	v_add_u32_e32 v82, 0, v41
	v_ashrrev_i32_e32 v41, 31, v40
	v_readlane_b32 s85, v253, 55
	s_add_u32 s21, s84, s22
	v_lshlrev_b64 v[162:163], 11, v[40:41]
	s_addc_u32 s22, s85, s23
	s_movk_i32 s23, 0x90
	v_lshl_add_u64 v[40:41], s[6:7], 0, v[162:163]
	s_lshl_b32 s0, s0, 1
	v_mad_u64_u32 v[164:165], s[54:55], v74, s23, v[82:83]
	v_mad_u64_u32 v[166:167], s[54:55], v76, s23, v[82:83]
	v_mad_u64_u32 v[168:169], s[54:55], v78, s23, v[82:83]
	v_mad_u64_u32 v[170:171], s[54:55], v80, s23, v[82:83]
	v_lshl_add_u64 v[40:41], v[40:41], 0, s[0:1]
	v_lshlrev_b32_e32 v152, 1, v96
	global_load_dwordx4 v[0:3], v[32:33], off offset:272
	global_load_dwordx4 v[20:23], v[32:33], off offset:256
	global_load_dwordx4 v[4:7], v[34:35], off offset:272
	global_load_dwordx4 v[24:27], v[34:35], off offset:256
	global_load_dwordx4 v[8:11], v[36:37], off offset:272
	global_load_dwordx4 v[28:31], v[36:37], off offset:256
	global_load_dwordx4 v[12:15], v[38:39], off offset:272
	global_load_dwordx4 v[16:19], v[38:39], off offset:256
	v_lshl_add_u64 v[40:41], v[40:41], 0, v[152:153]
	s_mov_b64 s[54:55], 0x1b500000
	s_mov_b32 s23, 0x1b500000
	v_lshl_add_u64 v[172:173], v[40:41], 0, s[54:55]
	v_add_co_u32_e32 v40, vcc, s23, v40
	s_add_u32 s20, s21, s20
	s_nop 0
	v_addc_co_u32_e32 v41, vcc, 0, v41, vcc
	global_load_dwordx4 v[226:229], v[172:173], off
	global_load_dwordx4 v[230:233], v[172:173], off offset:64
	s_addc_u32 s21, s22, 0
	s_mov_b64 s[22:23], 0x1000
	v_readlane_b32 s73, v253, 43
	v_readlane_b32 s74, v253, 44
	v_readlane_b32 s75, v253, 45
	v_readlane_b32 s76, v253, 46
	v_readlane_b32 s77, v253, 47
	v_readlane_b32 s78, v253, 48
	v_readlane_b32 s79, v253, 49
	v_readlane_b32 s80, v253, 50
	v_readlane_b32 s81, v253, 51
	v_readlane_b32 s86, v253, 56
	v_readlane_b32 s87, v253, 57
	s_waitcnt vmcnt(10)
	v_cvt_pk_bf16_f32 v46, v46, v47
	v_cvt_pk_bf16_f32 v47, v48, v49
	v_cvt_pk_bf16_f32 v48, v42, v43
	v_cvt_pk_bf16_f32 v49, v44, v45
	v_cvt_pk_bf16_f32 v42, v54, v55
	v_cvt_pk_bf16_f32 v43, v56, v57
	v_cvt_pk_bf16_f32 v44, v50, v51
	v_cvt_pk_bf16_f32 v45, v52, v53
	ds_write_b128 v164, v[46:49]
	ds_write_b128 v166, v[42:45]
	v_cvt_pk_bf16_f32 v42, v62, v63
	v_cvt_pk_bf16_f32 v43, v64, v65
	v_cvt_pk_bf16_f32 v44, v58, v59
	v_cvt_pk_bf16_f32 v45, v60, v61
	ds_write_b128 v168, v[42:45]
	v_cvt_pk_bf16_f32 v42, v70, v71
	v_cvt_pk_bf16_f32 v43, v72, v73
	v_cvt_pk_bf16_f32 v44, v66, v67
	v_cvt_pk_bf16_f32 v45, v68, v69
	ds_write_b128 v170, v[42:45]
	global_load_dwordx4 v[234:237], v[172:173], off offset:128
	global_load_dwordx4 v[238:241], v[172:173], off offset:192
	global_load_dwordx4 v[88:91], v[32:33], off offset:528
	global_load_dwordx4 v[92:95], v[32:33], off offset:512
	global_load_dwordx4 v[72:75], v[34:35], off offset:528
	global_load_dwordx4 v[80:83], v[34:35], off offset:512
	global_load_dwordx4 v[64:67], v[36:37], off offset:528
	global_load_dwordx4 v[68:71], v[36:37], off offset:512
	global_load_dwordx4 v[76:79], v[38:39], off offset:528
	global_load_dwordx4 v[84:87], v[38:39], off offset:512
	s_waitcnt lgkmcnt(0)
	s_barrier
	s_waitcnt vmcnt(10)
	ds_read_b128 v[44:47], v193
	ds_read_b128 v[52:55], v193 offset:64
	ds_read_b128 v[48:51], v193 offset:2304
	v_cvt_pk_bf16_f32 v20, v20, v21
	v_cvt_pk_bf16_f32 v21, v22, v23
	v_cvt_pk_bf16_f32 v22, v0, v1
	v_cvt_pk_bf16_f32 v23, v2, v3
	v_cvt_pk_bf16_f32 v0, v24, v25
	v_cvt_pk_bf16_f32 v1, v26, v27
	v_cvt_pk_bf16_f32 v2, v4, v5
	v_cvt_pk_bf16_f32 v3, v6, v7
	s_waitcnt lgkmcnt(0)
	v_mfma_f32_16x16x32_bf16 v[44:47], v[44:47], v[226:229], 0
	v_mfma_f32_16x16x32_bf16 v[40:43], v[48:51], v[226:229], 0
	v_mfma_f32_16x16x32_bf16 v[218:221], v[52:55], v[230:233], v[44:47]
	s_nop 3
	ds_read_b128 v[44:47], v193 offset:2368
	s_waitcnt lgkmcnt(0)
	s_barrier
	ds_write_b128 v164, v[20:23]
	ds_write_b128 v166, v[0:3]
	v_cvt_pk_bf16_f32 v0, v28, v29
	v_cvt_pk_bf16_f32 v1, v30, v31
	v_cvt_pk_bf16_f32 v2, v8, v9
	v_cvt_pk_bf16_f32 v3, v10, v11
	ds_write_b128 v168, v[0:3]
	v_cvt_pk_bf16_f32 v0, v16, v17
	v_cvt_pk_bf16_f32 v1, v18, v19
	v_cvt_pk_bf16_f32 v2, v12, v13
	v_cvt_pk_bf16_f32 v3, v14, v15
	ds_write_b128 v170, v[0:3]
	v_mfma_f32_16x16x32_bf16 v[222:225], v[44:47], v[230:233], v[40:43]
	global_load_dwordx4 v[226:229], v[172:173], off offset:256
	global_load_dwordx4 v[230:233], v[172:173], off offset:320
	global_load_dwordx4 v[56:59], v[32:33], off offset:784
	global_load_dwordx4 v[60:63], v[32:33], off offset:768
	global_load_dwordx4 v[48:51], v[34:35], off offset:784
	global_load_dwordx4 v[52:55], v[34:35], off offset:768
	global_load_dwordx4 v[40:43], v[36:37], off offset:784
	global_load_dwordx4 v[44:47], v[36:37], off offset:768
	s_nop 0
	global_load_dwordx4 v[32:35], v[38:39], off offset:784
	s_nop 0
	global_load_dwordx4 v[36:39], v[38:39], off offset:768
	s_waitcnt lgkmcnt(0)
	s_barrier
	s_waitcnt vmcnt(0)
	ds_read_b128 v[4:7], v193
	ds_read_b128 v[12:15], v193 offset:64
	ds_read_b128 v[8:11], v193 offset:2304
	s_waitcnt lgkmcnt(0)
	v_mfma_f32_16x16x32_bf16 v[4:7], v[4:7], v[234:237], v[218:221]
	v_cvt_pk_bf16_f32 v60, v60, v61
	v_cvt_pk_bf16_f32 v61, v62, v63
	v_cvt_pk_bf16_f32 v62, v56, v57
	v_mfma_f32_16x16x32_bf16 v[0:3], v[8:11], v[234:237], v[222:225]
	v_cvt_pk_bf16_f32 v63, v58, v59
	v_cvt_pk_bf16_f32 v52, v52, v53
	v_cvt_pk_bf16_f32 v53, v54, v55
	v_cvt_pk_bf16_f32 v54, v48, v49
	v_cvt_pk_bf16_f32 v55, v50, v51
	v_cvt_pk_bf16_f32 v44, v44, v45
	v_cvt_pk_bf16_f32 v45, v46, v47
	v_cvt_pk_bf16_f32 v46, v40, v41
	v_cvt_pk_bf16_f32 v47, v42, v43
	v_cvt_pk_bf16_f32 v36, v36, v37
	v_cvt_pk_bf16_f32 v37, v38, v39
	v_cvt_pk_bf16_f32 v38, v32, v33
	s_waitcnt lgkmcnt(0)
	v_mfma_f32_16x16x32_bf16 v[218:221], v[12:15], v[238:241], v[4:7]
	s_nop 2
	ds_read_b128 v[4:7], v193 offset:2368
	s_waitcnt lgkmcnt(0)
	s_barrier
	v_mfma_f32_16x16x32_bf16 v[222:225], v[4:7], v[238:241], v[0:3]
	s_nop 2
	v_cvt_pk_bf16_f32 v0, v92, v93
	v_cvt_pk_bf16_f32 v1, v94, v95
	v_cvt_pk_bf16_f32 v2, v88, v89
	v_cvt_pk_bf16_f32 v3, v90, v91
	ds_write_b128 v164, v[0:3]
	v_cvt_pk_bf16_f32 v0, v80, v81
	v_cvt_pk_bf16_f32 v1, v82, v83
	v_cvt_pk_bf16_f32 v2, v72, v73
	v_cvt_pk_bf16_f32 v3, v74, v75
	ds_write_b128 v166, v[0:3]
	v_cvt_pk_bf16_f32 v0, v68, v69
	v_cvt_pk_bf16_f32 v1, v70, v71
	v_cvt_pk_bf16_f32 v2, v64, v65
	v_cvt_pk_bf16_f32 v3, v66, v67
	ds_write_b128 v168, v[0:3]
	v_cvt_pk_bf16_f32 v0, v84, v85
	v_cvt_pk_bf16_f32 v1, v86, v87
	v_cvt_pk_bf16_f32 v2, v76, v77
	v_cvt_pk_bf16_f32 v3, v78, v79
	ds_write_b128 v170, v[0:3]
	v_lshlrev_b32_e32 v0, 11, v216
	v_lshlrev_b32_e32 v2, 3, v216
	v_and_b32_e32 v152, 0xfe000, v0
	v_and_b32_e32 v82, 24, v2
	v_lshl_add_u64 v[0:1], s[20:21], 0, v[152:153]
	v_ashrrev_i32_e32 v83, 31, v82
	v_lshl_add_u64 v[72:73], v[82:83], 2, v[0:1]
	s_movk_i32 s20, 0x1000
	v_add_co_u32_e32 v76, vcc, s20, v72
	v_lshl_add_u64 v[2:3], v[72:73], 0, s[22:23]
	s_nop 0
	v_addc_co_u32_e32 v77, vcc, 0, v73, vcc
	global_load_dwordx4 v[234:237], v[172:173], off offset:384
	global_load_dwordx4 v[238:241], v[172:173], off offset:448
	global_load_dwordx4 v[16:19], v[72:73], off offset:16
	global_load_dwordx4 v[20:23], v[72:73], off
	global_load_dwordx4 v[28:31], v[76:77], off
	global_load_dwordx4 v[24:27], v[2:3], off offset:16
	v_lshlrev_b32_e32 v2, 3, v216
	v_and_or_b32 v80, v2, 24, 32
	v_ashrrev_i32_e32 v81, 31, v80
	v_lshl_add_u64 v[74:75], v[80:81], 2, v[0:1]
	v_add_co_u32_e32 v78, vcc, s20, v74
	v_lshl_add_u64 v[8:9], v[74:75], 0, s[22:23]
	s_nop 0
	v_addc_co_u32_e32 v79, vcc, 0, v75, vcc
	global_load_dwordx4 v[0:3], v[74:75], off offset:16
	global_load_dwordx4 v[4:7], v[74:75], off
	global_load_dwordx4 v[12:15], v[78:79], off
	s_nop 0
	global_load_dwordx4 v[8:11], v[8:9], off offset:16
	s_waitcnt lgkmcnt(0)
	s_barrier
	s_waitcnt vmcnt(10)
	ds_read_b128 v[68:71], v193
	ds_read_b128 v[88:91], v193 offset:64
	ds_read_b128 v[84:87], v193 offset:2304
	s_waitcnt lgkmcnt(0)
	v_mfma_f32_16x16x32_bf16 v[68:71], v[68:71], v[226:229], v[218:221]
	v_cvt_pk_bf16_f32 v39, v34, v35
	s_mov_b64 s[20:21], 0x1100
	v_lshl_add_u64 v[32:33], v[72:73], 0, s[20:21]
	v_mfma_f32_16x16x32_bf16 v[64:67], v[84:87], v[226:229], v[222:225]
	v_mfma_f32_16x16x32_bf16 v[68:71], v[88:91], v[230:233], v[68:71]
	ds_read_b128 v[88:91], v193 offset:2368
	s_waitcnt lgkmcnt(0)
	s_barrier
	ds_write_b128 v164, v[60:63]
	ds_write_b128 v166, v[52:55]
	ds_write_b128 v168, v[44:47]
	ds_write_b128 v170, v[36:39]
	v_lshl_add_u64 v[44:45], v[74:75], 0, s[20:21]
	v_mfma_f32_16x16x32_bf16 v[64:67], v[88:91], v[230:233], v[64:67]
	global_load_dwordx4 v[48:51], v[72:73], off offset:272
	global_load_dwordx4 v[60:63], v[72:73], off offset:256
	global_load_dwordx4 v[56:59], v[76:77], off offset:256
	global_load_dwordx4 v[52:55], v[32:33], off offset:16
	s_nop 0
	global_load_dwordx4 v[32:35], v[74:75], off offset:272
	global_load_dwordx4 v[36:39], v[74:75], off offset:256
	global_load_dwordx4 v[40:43], v[78:79], off offset:256
	s_nop 0
	global_load_dwordx4 v[44:47], v[44:45], off offset:16
	s_waitcnt lgkmcnt(0)
	s_barrier
	s_waitcnt vmcnt(8)
	ds_read_b128 v[88:91], v193
	s_waitcnt lgkmcnt(0)
	v_mfma_f32_16x16x32_bf16 v[68:71], v[88:91], v[234:237], v[68:71]
	ds_read_b128 v[88:91], v193 offset:2304
	s_waitcnt lgkmcnt(0)
	v_mfma_f32_16x16x32_bf16 v[64:67], v[88:91], v[234:237], v[64:67]
	ds_read_b128 v[88:91], v193 offset:64
	s_waitcnt lgkmcnt(0)
	v_mfma_f32_16x16x32_bf16 v[68:71], v[88:91], v[238:241], v[68:71]
	ds_read_b128 v[88:91], v193 offset:2368
	s_nop 6
	v_max_f32_e32 v81, v69, v69
	s_waitcnt lgkmcnt(0)
	v_mfma_f32_16x16x32_bf16 v[64:67], v[88:91], v[238:241], v[64:67]
	v_max_f32_e32 v83, v68, v68
	v_max_f32_e32 v81, v83, v81
	v_max_f32_e32 v83, v71, v71
	v_max_f32_e32 v84, v70, v70
	v_max_f32_e32 v83, v84, v83
	s_nop 2
	v_max_f32_e32 v84, v67, v67
	v_max_f32_e32 v85, v66, v66
	v_max_f32_e32 v84, v85, v84
	v_max3_f32 v84, v64, v65, v84
	v_max3_f32 v83, v81, v83, v84
	v_and_b32_e32 v84, 64, v188
	v_xor_b32_e32 v81, 16, v188
	v_add_u32_e32 v84, 64, v84
	v_cmp_lt_i32_e32 vcc, v81, v84
	s_nop 1
	v_cndmask_b32_e32 v81, v188, v81, vcc
	v_lshlrev_b32_e32 v81, 2, v81
	ds_bpermute_b32 v85, v81, v83
	s_waitcnt lgkmcnt(0)
	v_max_f32_e32 v85, v85, v85
	v_max_f32_e32 v85, v83, v85
	v_xor_b32_e32 v83, 32, v188
	v_cmp_lt_i32_e32 vcc, v83, v84
	s_nop 1
	v_cndmask_b32_e32 v83, v188, v83, vcc
	v_lshlrev_b32_e32 v83, 2, v83
	ds_bpermute_b32 v84, v83, v85
	s_waitcnt lgkmcnt(0)
	v_max_f32_e32 v84, v84, v84
	v_max_f32_e32 v84, v85, v84
	s_and_saveexec_b64 s[20:21], s[8:9]
	ds_write_b32 v212, v84 offset:45312
	s_or_b64 exec, exec, s[20:21]
	v_add_u32_e32 v88, 0xb000, v174
	s_waitcnt lgkmcnt(0)
	s_barrier
	ds_read2_b32 v[86:87], v88 offset0:64 offset1:80
	s_waitcnt lgkmcnt(0)
	v_max3_f32 v86, v84, v86, v87
	ds_read2_b32 v[84:85], v88 offset0:96 offset1:112
	s_waitcnt lgkmcnt(0)
	v_max3_f32 v86, v86, v84, v85
	ds_read2_b32 v[84:85], v88 offset0:128 offset1:144
	s_waitcnt lgkmcnt(0)
	v_max3_f32 v86, v86, v84, v85
	ds_read2_b32 v[84:85], v88 offset0:160 offset1:176
	s_waitcnt lgkmcnt(0)
	v_max3_f32 v84, v86, v84, v85
	v_sub_f32_e32 v68, v68, v84
	v_mul_f32_e32 v68, 0x3fb8aa3b, v68
	v_sub_f32_e32 v69, v69, v84
	v_exp_f32_e32 v68, v68
	v_mul_f32_e32 v69, 0x3fb8aa3b, v69
	v_sub_f32_e32 v70, v70, v84
	v_exp_f32_e32 v69, v69
	v_mul_f32_e32 v70, 0x3fb8aa3b, v70
	v_sub_f32_e32 v71, v71, v84
	v_exp_f32_e32 v70, v70
	v_mul_f32_e32 v71, 0x3fb8aa3b, v71
	v_sub_f32_e32 v64, v64, v84
	v_exp_f32_e32 v71, v71
	v_mul_f32_e32 v64, 0x3fb8aa3b, v64
	v_sub_f32_e32 v65, v65, v84
	v_add_f32_e32 v85, 0, v68
	v_exp_f32_e32 v64, v64
	v_mul_f32_e32 v65, 0x3fb8aa3b, v65
	v_sub_f32_e32 v66, v66, v84
	v_add_f32_e32 v85, v69, v85
	v_exp_f32_e32 v65, v65
	v_mul_f32_e32 v66, 0x3fb8aa3b, v66
	v_sub_f32_e32 v67, v67, v84
	v_add_f32_e32 v85, v70, v85
	v_exp_f32_e32 v66, v66
	v_mul_f32_e32 v67, 0x3fb8aa3b, v67
	v_add_f32_e32 v85, v71, v85
	v_exp_f32_e32 v67, v67
	v_cvt_pk_bf16_f32 v68, v68, v69
	v_cvt_pk_bf16_f32 v69, v70, v71
	v_add_f32_e32 v70, v64, v85
	v_add_f32_e32 v70, v65, v70
	v_add_f32_e32 v70, v66, v70
	v_add_f32_e32 v70, v67, v70
	v_cvt_pk_bf16_f32 v64, v64, v65
	v_cvt_pk_bf16_f32 v65, v66, v67
	ds_write2_b64 v213, v[68:69], v[64:65] offset1:4
	ds_bpermute_b32 v64, v81, v70
	s_waitcnt lgkmcnt(0)
	v_add_f32_e32 v64, v70, v64
	ds_bpermute_b32 v65, v83, v64
	s_and_saveexec_b64 s[20:21], s[8:9]
	s_cbranch_execz .LBB0_161
	s_waitcnt lgkmcnt(0)
	v_add_f32_e32 v64, v64, v65
	ds_write_b32 v212, v64 offset:45824
.LBB0_161:
	s_or_b64 exec, exec, s[20:21]
	v_mov_b32_e32 v64, v216
	s_add_u32 s20, s6, 0x17100000
	v_and_b32_e32 v64, 0x1fc, v64
	s_movk_i32 s6, 0x210
	v_add_u32_e32 v64, 0, v64
	v_cvt_pk_bf16_f32 v20, v20, v21
	v_cvt_pk_bf16_f32 v21, v22, v23
	v_cvt_pk_bf16_f32 v22, v24, v25
	v_mul_lo_u32 v24, v82, s6
	v_cvt_pk_bf16_f32 v16, v16, v17
	v_cvt_pk_bf16_f32 v17, v18, v19
	v_cvt_pk_bf16_f32 v18, v28, v29
	v_add_u32_e32 v69, v64, v24
	v_and_b32_e32 v24, 0xffff, v20
	v_lshrrev_b32_e32 v20, 16, v20
	v_lshl_or_b32 v24, v18, 16, v24
	v_and_or_b32 v18, v18, s59, v20
	v_cvt_pk_bf16_f32 v19, v30, v31
	ds_write2_b32 v69, v24, v18 offset1:132
	v_and_b32_e32 v18, 0xffff, v21
	v_lshrrev_b32_e32 v20, 16, v21
	v_lshl_or_b32 v18, v19, 16, v18
	v_and_or_b32 v19, v19, s59, v20
	v_add_u32_e32 v70, 0x400, v69
	ds_write2_b32 v70, v18, v19 offset0:8 offset1:140
	v_and_b32_e32 v18, 0xffff, v16
	v_lshrrev_b32_e32 v16, 16, v16
	v_lshl_or_b32 v18, v22, 16, v18
	v_and_or_b32 v16, v22, s59, v16
	v_add_u32_e32 v81, 0x800, v69
	v_cvt_pk_bf16_f32 v4, v4, v5
	v_cvt_pk_bf16_f32 v5, v6, v7
	v_cvt_pk_bf16_f32 v6, v8, v9
	v_mul_lo_u32 v8, v80, s6
	v_cvt_pk_bf16_f32 v23, v26, v27
	ds_write2_b32 v81, v18, v16 offset0:16 offset1:148
	v_and_b32_e32 v16, 0xffff, v17
	v_lshrrev_b32_e32 v17, 16, v17
	v_cvt_pk_bf16_f32 v0, v0, v1
	v_cvt_pk_bf16_f32 v1, v2, v3
	v_cvt_pk_bf16_f32 v2, v12, v13
	v_add_u32_e32 v71, v64, v8
	v_and_b32_e32 v8, 0xffff, v4
	v_lshrrev_b32_e32 v4, 16, v4
	v_lshl_or_b32 v16, v23, 16, v16
	v_and_or_b32 v17, v23, s59, v17
	v_add_u32_e32 v82, 0xc00, v69
	v_lshl_or_b32 v8, v2, 16, v8
	v_and_or_b32 v2, v2, s59, v4
	ds_write2_b32 v82, v16, v17 offset0:24 offset1:156
	v_cvt_pk_bf16_f32 v3, v14, v15
	ds_write2_b32 v71, v8, v2 offset1:132
	v_and_b32_e32 v2, 0xffff, v5
	v_lshrrev_b32_e32 v4, 16, v5
	v_lshl_or_b32 v2, v3, 16, v2
	v_and_or_b32 v3, v3, s59, v4
	v_add_u32_e32 v80, 0x400, v71
	ds_write2_b32 v80, v2, v3 offset0:8 offset1:140
	v_and_b32_e32 v2, 0xffff, v0
	v_lshrrev_b32_e32 v0, 16, v0
	v_lshl_or_b32 v2, v6, 16, v2
	v_and_or_b32 v0, v6, s59, v0
	v_add_u32_e32 v83, 0x800, v71
	v_cvt_pk_bf16_f32 v7, v10, v11
	ds_write2_b32 v83, v2, v0 offset0:16 offset1:148
	v_and_b32_e32 v0, 0xffff, v1
	v_lshrrev_b32_e32 v1, 16, v1
	s_addc_u32 s21, s7, 0
	v_lshl_or_b32 v0, v7, 16, v0
	v_and_or_b32 v1, v7, s59, v1
	v_add_u32_e32 v84, 0xc00, v71
	s_mov_b64 s[6:7], 0x1200
	ds_write2_b32 v84, v0, v1 offset0:24 offset1:156
	v_lshl_add_u64 v[0:1], v[72:73], 0, s[6:7]
	global_load_dwordx4 v[16:19], v[72:73], off offset:528
	global_load_dwordx4 v[28:31], v[72:73], off offset:512
	global_load_dwordx4 v[24:27], v[76:77], off offset:512
	global_load_dwordx4 v[20:23], v[0:1], off offset:16
	s_nop 0
	global_load_dwordx4 v[0:3], v[74:75], off offset:528
	global_load_dwordx4 v[4:7], v[74:75], off offset:512
	v_lshl_add_u64 v[12:13], v[74:75], 0, s[6:7]
	global_load_dwordx4 v[8:11], v[78:79], off offset:512
	s_nop 0
	global_load_dwordx4 v[12:15], v[12:13], off offset:16
	v_add_u32_e32 v66, 0xb000, v194
	s_waitcnt lgkmcnt(0)
	s_barrier
	ds_read2_b32 v[64:65], v66 offset0:192 offset1:208
	v_readlane_b32 s84, v254, 51
	v_readlane_b32 s83, v254, 49
	v_readlane_b32 s86, v254, 50
	s_mov_b32 s87, 0xf800000
	s_waitcnt lgkmcnt(0)
	v_add_f32_e32 v64, 0, v64
	v_add_f32_e32 v67, v64, v65
	ds_read2_b32 v[64:65], v66 offset0:224 offset1:240
	v_readlane_b32 s85, v254, 52
	v_readlane_b32 s72, v254, 57
	s_mov_b64 s[80:81], s[64:65]
	s_mov_b64 s[78:79], s[66:67]
	s_waitcnt lgkmcnt(0)
	v_add_f32_e32 v64, v67, v64
	v_add_u32_e32 v67, 0xb400, v194
	v_add_f32_e32 v66, v64, v65
	ds_read2_b32 v[64:65], v67 offset1:16
	s_mov_b64 s[76:77], s[68:69]
	s_mov_b32 s69, s71
	s_waitcnt lgkmcnt(0)
	v_add_f32_e32 v64, v66, v64
	v_add_f32_e32 v66, v64, v65
	ds_read2_b32 v[64:65], v67 offset0:32 offset1:48
	s_waitcnt lgkmcnt(0)
	v_add_f32_e32 v64, v66, v64
	v_add_f32_e32 v64, v64, v65
	v_div_scale_f32 v65, s[6:7], v64, v64, 1.0
	v_rcp_f32_e32 v66, v65
	s_nop 0
	v_fma_f32 v67, -v65, v66, 1.0
	v_fmac_f32_e32 v66, v67, v66
	v_div_scale_f32 v67, vcc, 1.0, v64, 1.0
	v_mul_f32_e32 v68, v67, v66
	v_fma_f32 v78, -v65, v68, v67
	v_fmac_f32_e32 v68, v78, v66
	v_fma_f32 v65, -v65, v68, v67
	v_div_fmas_f32 v65, v65, v66, v68
	v_div_fixup_f32 v68, v65, v64, 1.0
	v_cndmask_b32_e64 v64, 0, 1, s[14:15]
	v_cmp_ne_u32_e64 s[6:7], 1, v64
	s_andn2_b64 vcc, exec, s[14:15]
	v_add_u32_e32 v78, v175, v99
	s_cbranch_vccnz .LBB0_165
	ds_read_b128 v[64:67], v214
	ds_read_b128 v[86:89], v78 offset:36864
	s_waitcnt lgkmcnt(0)
	v_mfma_f32_16x16x32_bf16 v[64:67], v[64:67], v[86:89], 0
	ds_read_b128 v[86:89], v214 offset:64
	ds_read_b128 v[90:93], v78 offset:36928
	s_waitcnt lgkmcnt(0)
	v_mfma_f32_16x16x32_bf16 v[64:67], v[86:89], v[90:93], v[64:67]
	ds_read_b128 v[86:89], v214 offset:128
	ds_read_b128 v[90:93], v78 offset:36992
	s_waitcnt lgkmcnt(0)
	v_mfma_f32_16x16x32_bf16 v[64:67], v[86:89], v[90:93], v[64:67]
	ds_read_b128 v[86:89], v214 offset:192
	ds_read_b128 v[90:93], v78 offset:37056
	s_waitcnt lgkmcnt(0)
	v_mfma_f32_16x16x32_bf16 v[64:67], v[86:89], v[90:93], v[64:67]
	ds_read_b128 v[86:89], v214 offset:256
	ds_read_b128 v[90:93], v78 offset:37120
	s_waitcnt lgkmcnt(0)
	v_mfma_f32_16x16x32_bf16 v[64:67], v[86:89], v[90:93], v[64:67]
	ds_read_b128 v[86:89], v214 offset:320
	ds_read_b128 v[90:93], v78 offset:37184
	s_waitcnt lgkmcnt(0)
	v_mfma_f32_16x16x32_bf16 v[64:67], v[86:89], v[90:93], v[64:67]
	ds_read_b128 v[86:89], v214 offset:384
	ds_read_b128 v[90:93], v78 offset:37248
	s_waitcnt lgkmcnt(0)
	v_mfma_f32_16x16x32_bf16 v[64:67], v[86:89], v[90:93], v[64:67]
	ds_read_b128 v[86:89], v214 offset:448
	ds_read_b128 v[90:93], v78 offset:37312
	s_waitcnt lgkmcnt(0)
	v_mfma_f32_16x16x32_bf16 v[64:67], v[86:89], v[90:93], v[64:67]
	s_and_saveexec_b64 s[22:23], s[4:5]
	s_cbranch_execz .LBB0_164
	s_nop 5
	v_pk_mul_f32 v[64:65], v[68:69], v[64:65] op_sel_hi:[0,1]
	v_pk_mul_f32 v[66:67], v[68:69], v[66:67] op_sel_hi:[0,1]
	v_cvt_pk_bf16_f32 v64, v64, v65
	v_cvt_pk_bf16_f32 v65, v66, v67
	v_lshl_add_u64 v[66:67], s[20:21], 0, v[162:163]
	v_lshl_add_u64 v[66:67], v[66:67], 0, s[0:1]
	v_lshl_add_u64 v[66:67], s[16:17], 1, v[66:67]
	v_lshlrev_b32_e32 v152, 1, v98
	v_lshl_add_u64 v[66:67], v[66:67], 0, v[152:153]
	flat_store_dwordx2 v[66:67], v[64:65]
